# background conversion delay 2 x s_sleep 90 instead of 2 x 64
# speedup vs baseline: 1.0048x; 1.0000x over previous
; #define LAS __attribute__((address_space(3)))
; __device__ __forceinline__ void cv_background(Frame& F, const CvPtrs& P, int s) {
;     int tv = threadIdx.x; asm volatile("" : "+v"(tv));
;     const int w = __builtin_amdgcn_readfirstlane(tv >> 6) - 1, lane = tv & 63, nbw = F.G * (NWAVES - 1);
;     LAS float* scr = (LAS float*)(F.lds + RING_OFF + (w + 1) * 16384);
;     const int sh_ = cv_bg_share(s), hi = (sh_ + 1) * CV_BG_PER < CV_BG_TOTAL ? (sh_ + 1) * CV_BG_PER : CV_BG_TOTAL;
;     for (int j = sh_ * CV_BG_PER + F.vcu * (NWAVES - 1) + w; j < hi; j += nbw) {
;         if (j < BG_L0A) cv_dispatch(P, F.ws, F.out, 0, CV_BG0 + j, scr, lane);
;         else if (j < BG_L0A + BG_P_ITEMS) cv_p_item(F.ws, P.p + (size_t)M * PLE, j - BG_L0A, lane);
;         else if (j < BG_L1_AT) cv_dispatch(P, F.ws, F.out, 0, CV_BG0 + j - BG_P_ITEMS, scr, lane);
;         else { const int jj = j - BG_L1_AT; cv_dispatch(P, F.ws, F.out, 1, jj < CI_IN ? jj : (jj < CI_IN + CI_PL ? CV_NITEMS - CI_PL + (jj - CI_IN) : jj - CI_PL), scr, lane); }
;     }
; }
; __device__ __forceinline__ void xcd_barrier_cv(const XcdBarrier& b, Frame& F, const CvPtrs& P, int s, bool local) {
;     asm volatile("s_waitcnt vmcnt(0)" ::: "memory");
;     __syncthreads();
;     if (threadIdx.x < 64) { if (threadIdx.x == 0) { if (local) xcc_barrier_thread0(b); else xcd_barrier_thread0(b); } }
;     else if (cv_bg_share(s) >= 0 && cv_bg_share(s) < CV_BG_SHARES) cv_background(F, P, s);
;     __syncthreads();
; }
.LBB0_769:
	s_and_b64 vcc, exec, s[0:1]
	s_cbranch_vccz .LBB0_1015
	s_sleep 90
	s_sleep 90
	v_mov_b32_e32 v4, v0
	s_mov_b64 s[6:7], -1
	v_readfirstlane_b32 s8, v4
	s_mov_b64 s[0:1], 0
	s_cmp_lt_i32 s89, 5
	s_mov_b64 s[4:5], 0
	s_cbranch_scc1 .LBB0_787
	s_cmp_gt_i32 s89, 7
	s_cbranch_scc0 .LBB0_779
	s_cmp_gt_i32 s89, 8
	s_cbranch_scc0 .LBB0_776
	s_cmp_eq_u32 s89, 9
	s_mov_b64 s[4:5], -1
	s_cbranch_scc0 .LBB0_775
	s_mov_b64 s[4:5], 0
